# grid barrier: L1 invalidate (buffer_inv sc1) issued at arrival instead of after release; leader drops trailing vmcnt wait
# speedup vs baseline: 1.0103x; 1.0103x over previous
.LBB0_37:
	v_readlane_b32 s2, v254, 2
	s_lshl_b32 s2, s2, 8
	s_add_u32 s2, s90, s2
	s_addc_u32 s3, s91, 0
	v_mov_b32_e32 v1, 0x1000
	v_mov_b32_e32 v3, 1
	global_atomic_add v3, v1, v3, s[2:3] offset:1024 sc0
	v_cvt_f32_u32_e32 v1, v2
	v_sub_u32_e32 v4, 0, v2
	v_rcp_iflag_f32_e32 v1, v1
	s_nop 0
	v_mul_f32_e32 v1, 0x4f7ffffe, v1
	v_cvt_u32_f32_e32 v1, v1
	v_mul_lo_u32 v4, v4, v1
	v_mul_hi_u32 v4, v1, v4
	v_add_u32_e32 v1, v1, v4
	s_waitcnt vmcnt(0)
	v_mul_hi_u32 v1, v3, v1
	v_mul_lo_u32 v4, v1, v2
	v_sub_u32_e32 v4, v3, v4
	v_add_u32_e32 v5, 1, v1
	v_cmp_ge_u32_e32 vcc, v4, v2
	v_add_u32_e32 v3, 1, v3
	s_nop 0
	v_cndmask_b32_e32 v1, v1, v5, vcc
	v_sub_u32_e32 v5, v4, v2
	v_cndmask_b32_e32 v4, v4, v5, vcc
	v_add_u32_e32 v5, 1, v1
	v_cmp_ge_u32_e32 vcc, v4, v2
	s_nop 1
	v_cndmask_b32_e32 v1, v1, v5, vcc
	v_mul_lo_u32 v4, v2, v1
	v_add_u32_e32 v2, v4, v2
	v_cmp_ne_u32_e32 vcc, v3, v2
	s_and_saveexec_b64 s[4:5], vcc
	s_xor_b64 s[4:5], exec, s[4:5]
	s_cbranch_execz .LBB0_51
	buffer_inv sc1
	s_waitcnt lgkmcnt(0)
	v_mov_b32_e32 v0, 0x2000
	global_load_dword v0, v0, s[2:3] offset:1024 sc1
	s_add_u32 s8, s2, 0x2400
	s_addc_u32 s9, s3, 0
	s_waitcnt vmcnt(0)
	v_cmp_eq_u32_e32 vcc, v0, v1
	s_and_saveexec_b64 s[6:7], vcc
	s_cbranch_execz .LBB0_50
	s_mov_b32 s20, 1
	s_mov_b64 s[10:11], 0
	v_mov_b32_e32 v0, 0
	s_branch .LBB0_41

.LBB0_50:
	s_or_b64 exec, exec, s[6:7]
	s_waitcnt vmcnt(0)
	s_waitcnt vmcnt(0)
.LBB0_51:
	s_andn2_saveexec_b64 s[4:5], s[4:5]
	s_cbranch_execz .LBB0_69
	s_mov_b64 s[4:5], exec
	buffer_wbl2 sc1
	buffer_inv sc1
	s_waitcnt lgkmcnt(0)
	s_waitcnt vmcnt(0)
	v_mbcnt_lo_u32_b32 v1, s4, 0
	v_mbcnt_hi_u32_b32 v1, s5, v1
	v_cmp_eq_u32_e32 vcc, 0, v1
	s_and_saveexec_b64 s[6:7], vcc
	s_cbranch_execz .LBB0_54
	s_bcnt1_i32_b64 s4, s[4:5]
	v_mov_b32_e32 v2, 0x3000
	v_mov_b32_e32 v3, s4
	global_atomic_add v2, v2, v3, s[90:91] offset:1024 sc0

.LBB0_68:
	s_or_b64 exec, exec, s[4:5]
	v_mov_b32_e32 v0, 0x2000
	v_mov_b32_e32 v1, 1
	s_waitcnt vmcnt(0)
	global_atomic_add v0, v1, s[2:3] offset:1024

.LBB0_283:
	v_readlane_b32 s4, v254, 2
	s_lshl_b32 s4, s4, 8
	s_add_u32 s4, s90, s4
	s_addc_u32 s5, s91, 0
	v_mov_b32_e32 v1, 0x1000
	v_mov_b32_e32 v3, 1
	global_atomic_add v3, v1, v3, s[4:5] offset:1024 sc0
	v_cvt_f32_u32_e32 v1, v2
	v_sub_u32_e32 v4, 0, v2
	v_rcp_iflag_f32_e32 v1, v1
	s_nop 0
	v_mul_f32_e32 v1, 0x4f7ffffe, v1
	v_cvt_u32_f32_e32 v1, v1
	v_mul_lo_u32 v4, v4, v1
	v_mul_hi_u32 v4, v1, v4
	v_add_u32_e32 v1, v1, v4
	s_waitcnt vmcnt(0)
	v_mul_hi_u32 v1, v3, v1
	v_mul_lo_u32 v4, v1, v2
	v_sub_u32_e32 v4, v3, v4
	v_add_u32_e32 v5, 1, v1
	v_cmp_ge_u32_e32 vcc, v4, v2
	v_add_u32_e32 v3, 1, v3
	s_nop 0
	v_cndmask_b32_e32 v1, v1, v5, vcc
	v_sub_u32_e32 v5, v4, v2
	v_cndmask_b32_e32 v4, v4, v5, vcc
	v_add_u32_e32 v5, 1, v1
	v_cmp_ge_u32_e32 vcc, v4, v2
	s_nop 1
	v_cndmask_b32_e32 v1, v1, v5, vcc
	v_mul_lo_u32 v4, v2, v1
	v_add_u32_e32 v2, v4, v2
	v_cmp_ne_u32_e32 vcc, v3, v2
	s_and_saveexec_b64 s[6:7], vcc
	s_xor_b64 s[6:7], exec, s[6:7]
	s_cbranch_execz .LBB0_297
	buffer_inv sc1
	s_waitcnt lgkmcnt(0)
	v_mov_b32_e32 v0, 0x2000
	global_load_dword v0, v0, s[4:5] offset:1024 sc1
	s_add_u32 s10, s4, 0x2400
	s_addc_u32 s11, s5, 0
	s_waitcnt vmcnt(0)
	v_cmp_eq_u32_e32 vcc, v0, v1
	s_and_saveexec_b64 s[8:9], vcc
	s_cbranch_execz .LBB0_296
	s_mov_b32 s22, 1
	s_mov_b64 s[12:13], 0
	v_mov_b32_e32 v0, 0
	s_branch .LBB0_287

.LBB0_296:
	s_or_b64 exec, exec, s[8:9]
	s_waitcnt vmcnt(0)
	s_waitcnt vmcnt(0)
.LBB0_297:
	s_andn2_saveexec_b64 s[6:7], s[6:7]
	s_cbranch_execz .LBB0_315
	s_mov_b64 s[6:7], exec
	buffer_wbl2 sc1
	buffer_inv sc1
	s_waitcnt lgkmcnt(0)
	s_waitcnt vmcnt(0)
	v_mbcnt_lo_u32_b32 v1, s6, 0
	v_mbcnt_hi_u32_b32 v1, s7, v1
	v_cmp_eq_u32_e32 vcc, 0, v1
	s_and_saveexec_b64 s[8:9], vcc
	s_cbranch_execz .LBB0_300
	s_bcnt1_i32_b64 s6, s[6:7]
	v_mov_b32_e32 v2, 0x3000
	v_mov_b32_e32 v3, s6
	global_atomic_add v2, v2, v3, s[90:91] offset:1024 sc0

.LBB0_314:
	s_or_b64 exec, exec, s[6:7]
	v_mov_b32_e32 v0, 0x2000
	v_mov_b32_e32 v1, 1
	s_waitcnt vmcnt(0)
	global_atomic_add v0, v1, s[4:5] offset:1024

.LBB0_512:
	v_readlane_b32 s2, v254, 2
	s_lshl_b32 s2, s2, 8
	s_add_u32 s2, s90, s2
	s_addc_u32 s3, s91, 0
	v_mov_b32_e32 v1, 0x1000
	v_mov_b32_e32 v3, 1
	global_atomic_add v3, v1, v3, s[2:3] offset:1024 sc0
	v_cvt_f32_u32_e32 v1, v2
	v_sub_u32_e32 v4, 0, v2
	v_rcp_iflag_f32_e32 v1, v1
	s_nop 0
	v_mul_f32_e32 v1, 0x4f7ffffe, v1
	v_cvt_u32_f32_e32 v1, v1
	v_mul_lo_u32 v4, v4, v1
	v_mul_hi_u32 v4, v1, v4
	v_add_u32_e32 v1, v1, v4
	s_waitcnt vmcnt(0)
	v_mul_hi_u32 v1, v3, v1
	v_mul_lo_u32 v4, v1, v2
	v_sub_u32_e32 v4, v3, v4
	v_add_u32_e32 v5, 1, v1
	v_cmp_ge_u32_e32 vcc, v4, v2
	v_add_u32_e32 v3, 1, v3
	s_nop 0
	v_cndmask_b32_e32 v1, v1, v5, vcc
	v_sub_u32_e32 v5, v4, v2
	v_cndmask_b32_e32 v4, v4, v5, vcc
	v_add_u32_e32 v5, 1, v1
	v_cmp_ge_u32_e32 vcc, v4, v2
	s_nop 1
	v_cndmask_b32_e32 v1, v1, v5, vcc
	v_mul_lo_u32 v4, v2, v1
	v_add_u32_e32 v2, v4, v2
	v_cmp_ne_u32_e32 vcc, v3, v2
	s_and_saveexec_b64 s[4:5], vcc
	s_xor_b64 s[4:5], exec, s[4:5]
	s_cbranch_execz .LBB0_526
	buffer_inv sc1
	s_waitcnt lgkmcnt(0)
	v_mov_b32_e32 v0, 0x2000
	global_load_dword v0, v0, s[2:3] offset:1024 sc1
	s_add_u32 s8, s2, 0x2400
	s_addc_u32 s9, s3, 0
	s_waitcnt vmcnt(0)
	v_cmp_eq_u32_e32 vcc, v0, v1
	s_and_saveexec_b64 s[6:7], vcc
	s_cbranch_execz .LBB0_525
	s_mov_b32 s22, 1
	s_mov_b64 s[12:13], 0
	v_mov_b32_e32 v0, 0
	s_branch .LBB0_516

.LBB0_747:
	v_readlane_b32 s2, v254, 2
	s_lshl_b32 s2, s2, 8
	s_add_u32 s2, s90, s2
	s_addc_u32 s3, s91, 0
	v_mov_b32_e32 v1, 0x1000
	v_mov_b32_e32 v3, 1
	global_atomic_add v3, v1, v3, s[2:3] offset:1024 sc0
	v_cvt_f32_u32_e32 v1, v2
	v_sub_u32_e32 v4, 0, v2
	v_rcp_iflag_f32_e32 v1, v1
	s_nop 0
	v_mul_f32_e32 v1, 0x4f7ffffe, v1
	v_cvt_u32_f32_e32 v1, v1
	v_mul_lo_u32 v4, v4, v1
	v_mul_hi_u32 v4, v1, v4
	v_add_u32_e32 v1, v1, v4
	s_waitcnt vmcnt(0)
	v_mul_hi_u32 v1, v3, v1
	v_mul_lo_u32 v4, v1, v2
	v_sub_u32_e32 v4, v3, v4
	v_add_u32_e32 v5, 1, v1
	v_cmp_ge_u32_e32 vcc, v4, v2
	v_add_u32_e32 v3, 1, v3
	s_nop 0
	v_cndmask_b32_e32 v1, v1, v5, vcc
	v_sub_u32_e32 v5, v4, v2
	v_cndmask_b32_e32 v4, v4, v5, vcc
	v_add_u32_e32 v5, 1, v1
	v_cmp_ge_u32_e32 vcc, v4, v2
	s_nop 1
	v_cndmask_b32_e32 v1, v1, v5, vcc
	v_mul_lo_u32 v4, v2, v1
	v_add_u32_e32 v2, v4, v2
	v_cmp_ne_u32_e32 vcc, v3, v2
	s_and_saveexec_b64 s[6:7], vcc
	s_xor_b64 s[6:7], exec, s[6:7]
	s_cbranch_execz .LBB0_761
	buffer_inv sc1
	s_waitcnt lgkmcnt(0)
	v_mov_b32_e32 v0, 0x2000
	global_load_dword v0, v0, s[2:3] offset:1024 sc1
	s_add_u32 s10, s2, 0x2400
	s_addc_u32 s11, s3, 0
	s_waitcnt vmcnt(0)
	v_cmp_eq_u32_e32 vcc, v0, v1
	s_and_saveexec_b64 s[8:9], vcc
	s_cbranch_execz .LBB0_760
	s_mov_b32 s22, 1
	s_mov_b64 s[12:13], 0
	v_mov_b32_e32 v0, 0
	s_branch .LBB0_751

.LBB0_778:
	s_or_b64 exec, exec, s[6:7]
	v_mov_b32_e32 v0, 0x2000
	v_mov_b32_e32 v1, 1
	s_waitcnt vmcnt(0)
	global_atomic_add v0, v1, s[2:3] offset:1024

.LBB0_843:
	v_readlane_b32 s2, v254, 2
	s_lshl_b32 s2, s2, 8
	s_add_u32 s2, s90, s2
	s_addc_u32 s3, s91, 0
	v_mov_b32_e32 v1, 0x1000
	v_mov_b32_e32 v3, 1
	global_atomic_add v3, v1, v3, s[2:3] offset:1024 sc0
	v_cvt_f32_u32_e32 v1, v2
	v_sub_u32_e32 v4, 0, v2
	v_rcp_iflag_f32_e32 v1, v1
	s_nop 0
	v_mul_f32_e32 v1, 0x4f7ffffe, v1
	v_cvt_u32_f32_e32 v1, v1
	v_mul_lo_u32 v4, v4, v1
	v_mul_hi_u32 v4, v1, v4
	v_add_u32_e32 v1, v1, v4
	s_waitcnt vmcnt(0)
	v_mul_hi_u32 v1, v3, v1
	v_mul_lo_u32 v4, v1, v2
	v_sub_u32_e32 v4, v3, v4
	v_add_u32_e32 v5, 1, v1
	v_cmp_ge_u32_e32 vcc, v4, v2
	v_add_u32_e32 v3, 1, v3
	s_nop 0
	v_cndmask_b32_e32 v1, v1, v5, vcc
	v_sub_u32_e32 v5, v4, v2
	v_cndmask_b32_e32 v4, v4, v5, vcc
	v_add_u32_e32 v5, 1, v1
	v_cmp_ge_u32_e32 vcc, v4, v2
	s_nop 1
	v_cndmask_b32_e32 v1, v1, v5, vcc
	v_mul_lo_u32 v4, v2, v1
	v_add_u32_e32 v2, v4, v2
	v_cmp_ne_u32_e32 vcc, v3, v2
	s_and_saveexec_b64 s[4:5], vcc
	s_xor_b64 s[4:5], exec, s[4:5]
	s_cbranch_execz .LBB0_857
	buffer_inv sc1
	s_waitcnt lgkmcnt(0)
	v_mov_b32_e32 v0, 0x2000
	global_load_dword v0, v0, s[2:3] offset:1024 sc1
	s_add_u32 s10, s2, 0x2400
	s_addc_u32 s11, s3, 0
	s_waitcnt vmcnt(0)
	v_cmp_eq_u32_e32 vcc, v0, v1
	s_and_saveexec_b64 s[8:9], vcc
	s_cbranch_execz .LBB0_856
	s_mov_b32 s22, 1
	s_mov_b64 s[12:13], 0
	v_mov_b32_e32 v0, 0
	s_branch .LBB0_847

.LBB0_857:
	s_andn2_saveexec_b64 s[4:5], s[4:5]
	s_cbranch_execz .LBB0_875
	s_mov_b64 s[4:5], exec
	buffer_wbl2 sc1
	buffer_inv sc1
	s_waitcnt lgkmcnt(0)
	s_waitcnt vmcnt(0)
	v_mbcnt_lo_u32_b32 v1, s4, 0
	v_mbcnt_hi_u32_b32 v1, s5, v1
	v_cmp_eq_u32_e32 vcc, 0, v1
	s_and_saveexec_b64 s[8:9], vcc
	s_cbranch_execz .LBB0_860
	s_bcnt1_i32_b64 s4, s[4:5]
	v_mov_b32_e32 v2, 0x3000
	v_mov_b32_e32 v3, s4
	global_atomic_add v2, v2, v3, s[90:91] offset:1024 sc0
